# conv remnant phase: boundary items and sample-row conv items spread over all workgroups (different waves) instead of 176 + 44 workgroups
# speedup vs baseline: 1.0410x; 1.0126x over previous
.LBB0_182:
	s_mul_i32 s2, s84, 0x160
	v_add_u32_e32 v0, s2, v241
	s_movk_i32 s2, 0x160
	v_cmp_gt_u32_e32 vcc, s2, v241
	s_and_saveexec_b64 s[4:5], vcc
	s_cbranch_execz .Lbnd_done
	s_load_dwordx4 s[8:11], s[54:55], 0xb8
	v_readlane_b32 s14, v253, 41
	s_add_u32 s6, s82, 0xd200000
	s_addc_u32 s7, s83, 0
	s_add_u32 s12, s6, 0x6000000
	s_addc_u32 s13, s7, 0
	v_lshrrev_b32_e32 v2, 5, v0
	s_mov_b32 s2, 0xba2e8ba3
	v_mul_hi_u32 v2, v2, s2
	v_lshrrev_b32_e32 v2, 3, v2
	v_mul_u32_u24_e32 v3, 0x160, v2
	v_sub_u32_e32 v3, v0, v3
	v_lshlrev_b32_e32 v6, 4, v3
	v_lshlrev_b32_e32 v7, 5, v3
	s_mul_i32 s15, s14, 0x10800
	s_mul_i32 s14, s14, 0x5800
	s_waitcnt lgkmcnt(0)
	s_add_u32 s8, s8, s15
	s_addc_u32 s9, s9, 0
	s_add_u32 s10, s10, s14
	s_addc_u32 s11, s11, 0
	global_load_dwordx4 v[16:19], v7, s[8:9] offset:0
	global_load_dwordx4 v[20:23], v7, s[8:9] offset:16
	v_add_u32_e32 v8, 0x2c00, v7
	global_load_dwordx4 v[48:51], v8, s[8:9]
	v_add_u32_e32 v8, 0x2c10, v7
	global_load_dwordx4 v[52:55], v8, s[8:9]
	v_add_u32_e32 v8, 0x5800, v7
	global_load_dwordx4 v[24:27], v8, s[8:9]
	v_add_u32_e32 v8, 0x5810, v7
	global_load_dwordx4 v[28:31], v8, s[8:9]
	v_add_u32_e32 v8, 0x8400, v7
	global_load_dwordx4 v[56:59], v8, s[8:9]
	v_add_u32_e32 v8, 0x8410, v7
	global_load_dwordx4 v[60:63], v8, s[8:9]
	v_add_u32_e32 v8, 0xb000, v7
	global_load_dwordx4 v[32:35], v8, s[8:9]
	v_add_u32_e32 v8, 0xb010, v7
	global_load_dwordx4 v[36:39], v8, s[8:9]
	v_add_u32_e32 v8, 0xdc00, v7
	global_load_dwordx4 v[64:67], v8, s[8:9]
	v_add_u32_e32 v8, 0xdc10, v7
	global_load_dwordx4 v[68:71], v8, s[8:9]
	global_load_dwordx4 v[40:43], v7, s[10:11] offset:0
	global_load_dwordx4 v[44:47], v7, s[10:11] offset:16
	v_add_u32_e32 v8, 0x2c00, v7
	global_load_dwordx4 v[72:75], v8, s[10:11]
	v_add_u32_e32 v8, 0x2c10, v7
	global_load_dwordx4 v[76:79], v8, s[10:11]
	v_lshlrev_b32_e32 v9, 2, v2
	v_mov_b64_e32 v[10:11], s[12:13]
	v_mad_u64_u32 v[10:11], s[2:3], v9, s91, v[10:11]
	v_mov_b32_e32 v12, v6
	v_mov_b32_e32 v13, 0
	v_lshl_add_u64 v[10:11], v[10:11], 0, v[12:13]
	v_mov_b32_e32 v80, 0
	v_mov_b32_e32 v81, 0
	v_mov_b32_e32 v82, 0
	v_mov_b32_e32 v83, 0
	v_mov_b32_e32 v84, 0
	v_mov_b32_e32 v85, 0
	v_mov_b32_e32 v86, 0
	v_mov_b32_e32 v87, 0
	v_mov_b32_e32 v96, 0
	v_mov_b32_e32 v97, 0
	v_mov_b32_e32 v98, 0
	v_mov_b32_e32 v99, 0
	v_mov_b32_e32 v100, 0
	v_mov_b32_e32 v101, 0
	v_mov_b32_e32 v102, 0
	v_mov_b32_e32 v103, 0
	global_load_dwordx4 v[88:91], v[10:11], off
	s_mov_b64 s[2:3], 0x1600
	v_lshl_add_u64 v[12:13], v[10:11], 0, s[2:3]
	global_load_dwordx4 v[104:107], v[12:13], off
	s_mov_b64 s[2:3], 0x2c00
	v_lshl_add_u64 v[14:15], v[10:11], 0, s[2:3]
	global_load_dwordx4 v[92:95], v[14:15], off
	s_mov_b64 s[2:3], 0x4200
	v_lshl_add_u64 v[14:15], v[10:11], 0, s[2:3]
	global_load_dwordx4 v[108:111], v[14:15], off
	v_and_b32_e32 v9, 0x7f, v2
	v_cmp_ne_u32_e32 vcc, 0, v9
	s_and_saveexec_b64 s[16:17], vcc
	s_mov_b64 s[2:3], 0x2c00
	v_mov_b32_e32 v14, v10
	v_mov_b32_e32 v15, v11
	v_subrev_co_u32_e32 v14, vcc, 0x2c00, v10
	v_subbrev_co_u32_e32 v15, vcc, 0, v11, vcc
	global_load_dwordx4 v[84:87], v[14:15], off
	s_mov_b64 s[2:3], 0x1600
	v_lshl_add_u64 v[12:13], v[14:15], 0, s[2:3]
	global_load_dwordx4 v[100:103], v[12:13], off
	v_subrev_co_u32_e32 v14, vcc, 0x5800, v10
	v_subbrev_co_u32_e32 v15, vcc, 0, v11, vcc
	global_load_dwordx4 v[80:83], v[14:15], off
	v_lshl_add_u64 v[12:13], v[14:15], 0, s[2:3]
	global_load_dwordx4 v[96:99], v[12:13], off
	s_or_b64 exec, exec, s[16:17]
	s_waitcnt vmcnt(0)
	v_lshlrev_b32_e32 v112, 16, v80
	v_and_b32_e32 v113, 0xffff0000, v80
	v_lshlrev_b32_e32 v114, 16, v81
	v_and_b32_e32 v115, 0xffff0000, v81
	v_lshlrev_b32_e32 v116, 16, v82
	v_and_b32_e32 v117, 0xffff0000, v82
	v_lshlrev_b32_e32 v118, 16, v83
	v_and_b32_e32 v119, 0xffff0000, v83
	v_lshlrev_b32_e32 v120, 16, v84
	v_and_b32_e32 v121, 0xffff0000, v84
	v_lshlrev_b32_e32 v122, 16, v85
	v_and_b32_e32 v123, 0xffff0000, v85
	v_lshlrev_b32_e32 v124, 16, v86
	v_and_b32_e32 v125, 0xffff0000, v86
	v_lshlrev_b32_e32 v126, 16, v87
	v_and_b32_e32 v127, 0xffff0000, v87
	v_lshlrev_b32_e32 v128, 16, v88
	v_and_b32_e32 v129, 0xffff0000, v88
	v_lshlrev_b32_e32 v130, 16, v89
	v_and_b32_e32 v131, 0xffff0000, v89
	v_lshlrev_b32_e32 v132, 16, v90
	v_and_b32_e32 v133, 0xffff0000, v90
	v_lshlrev_b32_e32 v134, 16, v91
	v_and_b32_e32 v135, 0xffff0000, v91
	v_lshlrev_b32_e32 v136, 16, v92
	v_and_b32_e32 v137, 0xffff0000, v92
	v_lshlrev_b32_e32 v138, 16, v93
	v_and_b32_e32 v139, 0xffff0000, v93
	v_lshlrev_b32_e32 v140, 16, v94
	v_and_b32_e32 v141, 0xffff0000, v94
	v_lshlrev_b32_e32 v142, 16, v95
	v_and_b32_e32 v143, 0xffff0000, v95
	v_lshlrev_b32_e32 v144, 16, v96
	v_and_b32_e32 v145, 0xffff0000, v96
	v_lshlrev_b32_e32 v146, 16, v97
	v_and_b32_e32 v147, 0xffff0000, v97
	v_lshlrev_b32_e32 v148, 16, v98
	v_and_b32_e32 v149, 0xffff0000, v98
	v_lshlrev_b32_e32 v150, 16, v99
	v_and_b32_e32 v151, 0xffff0000, v99
	v_lshlrev_b32_e32 v152, 16, v100
	v_and_b32_e32 v153, 0xffff0000, v100
	v_lshlrev_b32_e32 v154, 16, v101
	v_and_b32_e32 v155, 0xffff0000, v101
	v_lshlrev_b32_e32 v156, 16, v102
	v_and_b32_e32 v157, 0xffff0000, v102
	v_lshlrev_b32_e32 v158, 16, v103
	v_and_b32_e32 v159, 0xffff0000, v103
	v_lshlrev_b32_e32 v160, 16, v104
	v_and_b32_e32 v161, 0xffff0000, v104
	v_lshlrev_b32_e32 v162, 16, v105
	v_and_b32_e32 v163, 0xffff0000, v105
	v_lshlrev_b32_e32 v164, 16, v106
	v_and_b32_e32 v165, 0xffff0000, v106
	v_lshlrev_b32_e32 v166, 16, v107
	v_and_b32_e32 v167, 0xffff0000, v107
	v_lshlrev_b32_e32 v168, 16, v108
	v_and_b32_e32 v169, 0xffff0000, v108
	v_lshlrev_b32_e32 v170, 16, v109
	v_and_b32_e32 v171, 0xffff0000, v109
	v_lshlrev_b32_e32 v172, 16, v110
	v_and_b32_e32 v173, 0xffff0000, v110
	v_lshlrev_b32_e32 v174, 16, v111
	v_and_b32_e32 v175, 0xffff0000, v111
	v_pk_fma_f32 v[176:177], v[112:113], v[16:17], v[40:41]
	v_pk_fma_f32 v[176:177], v[120:121], v[24:25], v[176:177]
	v_pk_fma_f32 v[176:177], v[128:129], v[32:33], v[176:177]
	v_pk_fma_f32 v[184:185], v[120:121], v[16:17], v[40:41]
	v_pk_fma_f32 v[184:185], v[128:129], v[24:25], v[184:185]
	v_pk_fma_f32 v[184:185], v[136:137], v[32:33], v[184:185]
	v_pk_fma_f32 v[178:179], v[114:115], v[18:19], v[42:43]
	v_pk_fma_f32 v[178:179], v[122:123], v[26:27], v[178:179]
	v_pk_fma_f32 v[178:179], v[130:131], v[34:35], v[178:179]
	v_pk_fma_f32 v[186:187], v[122:123], v[18:19], v[42:43]
	v_pk_fma_f32 v[186:187], v[130:131], v[26:27], v[186:187]
	v_pk_fma_f32 v[186:187], v[138:139], v[34:35], v[186:187]
	v_pk_fma_f32 v[180:181], v[116:117], v[20:21], v[44:45]
	v_pk_fma_f32 v[180:181], v[124:125], v[28:29], v[180:181]
	v_pk_fma_f32 v[180:181], v[132:133], v[36:37], v[180:181]
	v_pk_fma_f32 v[188:189], v[124:125], v[20:21], v[44:45]
	v_pk_fma_f32 v[188:189], v[132:133], v[28:29], v[188:189]
	v_pk_fma_f32 v[188:189], v[140:141], v[36:37], v[188:189]
	v_pk_fma_f32 v[182:183], v[118:119], v[22:23], v[46:47]
	v_pk_fma_f32 v[182:183], v[126:127], v[30:31], v[182:183]
	v_pk_fma_f32 v[182:183], v[134:135], v[38:39], v[182:183]
	v_pk_fma_f32 v[190:191], v[126:127], v[22:23], v[46:47]
	v_pk_fma_f32 v[190:191], v[134:135], v[30:31], v[190:191]
	v_pk_fma_f32 v[190:191], v[142:143], v[38:39], v[190:191]
	v_pk_fma_f32 v[192:193], v[144:145], v[48:49], v[72:73]
	v_pk_fma_f32 v[192:193], v[152:153], v[56:57], v[192:193]
	v_pk_fma_f32 v[192:193], v[160:161], v[64:65], v[192:193]
	v_pk_fma_f32 v[200:201], v[152:153], v[48:49], v[72:73]
	v_pk_fma_f32 v[200:201], v[160:161], v[56:57], v[200:201]
	v_pk_fma_f32 v[200:201], v[168:169], v[64:65], v[200:201]
	v_pk_fma_f32 v[194:195], v[146:147], v[50:51], v[74:75]
	v_pk_fma_f32 v[194:195], v[154:155], v[58:59], v[194:195]
	v_pk_fma_f32 v[194:195], v[162:163], v[66:67], v[194:195]
	v_pk_fma_f32 v[202:203], v[154:155], v[50:51], v[74:75]
	v_pk_fma_f32 v[202:203], v[162:163], v[58:59], v[202:203]
	v_pk_fma_f32 v[202:203], v[170:171], v[66:67], v[202:203]
	v_pk_fma_f32 v[196:197], v[148:149], v[52:53], v[76:77]
	v_pk_fma_f32 v[196:197], v[156:157], v[60:61], v[196:197]
	v_pk_fma_f32 v[196:197], v[164:165], v[68:69], v[196:197]
	v_pk_fma_f32 v[204:205], v[156:157], v[52:53], v[76:77]
	v_pk_fma_f32 v[204:205], v[164:165], v[60:61], v[204:205]
	v_pk_fma_f32 v[204:205], v[172:173], v[68:69], v[204:205]
	v_pk_fma_f32 v[198:199], v[150:151], v[54:55], v[78:79]
	v_pk_fma_f32 v[198:199], v[158:159], v[62:63], v[198:199]
	v_pk_fma_f32 v[198:199], v[166:167], v[70:71], v[198:199]
	v_pk_fma_f32 v[206:207], v[158:159], v[54:55], v[78:79]
	v_pk_fma_f32 v[206:207], v[166:167], v[62:63], v[206:207]
	v_pk_fma_f32 v[206:207], v[174:175], v[70:71], v[206:207]
	s_mov_b32 s2, 0xbfb8aa3b
	s_mov_b32 s3, 0xbfb8aa3b
	v_pk_mul_f32 v[216:217], v[176:177], s[2:3]
	v_exp_f32_e32 v216, v216
	v_exp_f32_e32 v217, v217
	s_nop 0
	v_pk_add_f32 v[216:217], v[216:217], 1.0 op_sel_hi:[1,0]
	v_rcp_f32_e32 v216, v216
	v_rcp_f32_e32 v217, v217
	s_nop 0
	v_pk_mul_f32 v[216:217], v[216:217], v[176:177]
	v_pk_mul_f32 v[216:217], v[216:217], v[192:193]
	v_cvt_pk_bf16_f32 v208, v216, v217
	v_pk_mul_f32 v[216:217], v[178:179], s[2:3]
	v_exp_f32_e32 v216, v216
	v_exp_f32_e32 v217, v217
	s_nop 0
	v_pk_add_f32 v[216:217], v[216:217], 1.0 op_sel_hi:[1,0]
	v_rcp_f32_e32 v216, v216
	v_rcp_f32_e32 v217, v217
	s_nop 0
	v_pk_mul_f32 v[216:217], v[216:217], v[178:179]
	v_pk_mul_f32 v[216:217], v[216:217], v[194:195]
	v_cvt_pk_bf16_f32 v209, v216, v217
	v_pk_mul_f32 v[216:217], v[180:181], s[2:3]
	v_exp_f32_e32 v216, v216
	v_exp_f32_e32 v217, v217
	s_nop 0
	v_pk_add_f32 v[216:217], v[216:217], 1.0 op_sel_hi:[1,0]
	v_rcp_f32_e32 v216, v216
	v_rcp_f32_e32 v217, v217
	s_nop 0
	v_pk_mul_f32 v[216:217], v[216:217], v[180:181]
	v_pk_mul_f32 v[216:217], v[216:217], v[196:197]
	v_cvt_pk_bf16_f32 v210, v216, v217
	v_pk_mul_f32 v[216:217], v[182:183], s[2:3]
	v_exp_f32_e32 v216, v216
	v_exp_f32_e32 v217, v217
	s_nop 0
	v_pk_add_f32 v[216:217], v[216:217], 1.0 op_sel_hi:[1,0]
	v_rcp_f32_e32 v216, v216
	v_rcp_f32_e32 v217, v217
	s_nop 0
	v_pk_mul_f32 v[216:217], v[216:217], v[182:183]
	v_pk_mul_f32 v[216:217], v[216:217], v[198:199]
	v_cvt_pk_bf16_f32 v211, v216, v217
	v_pk_mul_f32 v[216:217], v[184:185], s[2:3]
	v_exp_f32_e32 v216, v216
	v_exp_f32_e32 v217, v217
	s_nop 0
	v_pk_add_f32 v[216:217], v[216:217], 1.0 op_sel_hi:[1,0]
	v_rcp_f32_e32 v216, v216
	v_rcp_f32_e32 v217, v217
	s_nop 0
	v_pk_mul_f32 v[216:217], v[216:217], v[184:185]
	v_pk_mul_f32 v[216:217], v[216:217], v[200:201]
	v_cvt_pk_bf16_f32 v212, v216, v217
	v_pk_mul_f32 v[216:217], v[186:187], s[2:3]
	v_exp_f32_e32 v216, v216
	v_exp_f32_e32 v217, v217
	s_nop 0
	v_pk_add_f32 v[216:217], v[216:217], 1.0 op_sel_hi:[1,0]
	v_rcp_f32_e32 v216, v216
	v_rcp_f32_e32 v217, v217
	s_nop 0
	v_pk_mul_f32 v[216:217], v[216:217], v[186:187]
	v_pk_mul_f32 v[216:217], v[216:217], v[202:203]
	v_cvt_pk_bf16_f32 v213, v216, v217
	v_pk_mul_f32 v[216:217], v[188:189], s[2:3]
	v_exp_f32_e32 v216, v216
	v_exp_f32_e32 v217, v217
	s_nop 0
	v_pk_add_f32 v[216:217], v[216:217], 1.0 op_sel_hi:[1,0]
	v_rcp_f32_e32 v216, v216
	v_rcp_f32_e32 v217, v217
	s_nop 0
	v_pk_mul_f32 v[216:217], v[216:217], v[188:189]
	v_pk_mul_f32 v[216:217], v[216:217], v[204:205]
	v_cvt_pk_bf16_f32 v214, v216, v217
	v_pk_mul_f32 v[216:217], v[190:191], s[2:3]
	v_exp_f32_e32 v216, v216
	v_exp_f32_e32 v217, v217
	s_nop 0
	v_pk_add_f32 v[216:217], v[216:217], 1.0 op_sel_hi:[1,0]
	v_rcp_f32_e32 v216, v216
	v_rcp_f32_e32 v217, v217
	s_nop 0
	v_pk_mul_f32 v[216:217], v[216:217], v[190:191]
	v_pk_mul_f32 v[216:217], v[216:217], v[206:207]
	v_cvt_pk_bf16_f32 v215, v216, v217
	v_lshlrev_b32_e32 v9, 6, v2
	v_mov_b64_e32 v[10:11], s[6:7]
	s_movk_i32 s2, 0x1600
	v_mad_u64_u32 v[10:11], s[16:17], v9, s2, v[10:11]
	v_mov_b32_e32 v12, v6
	v_mov_b32_e32 v13, 0
	v_lshl_add_u64 v[10:11], v[10:11], 0, v[12:13]
	global_store_dwordx4 v[10:11], v[208:211], off
	s_mov_b64 s[2:3], 0x1600
	v_lshl_add_u64 v[10:11], v[10:11], 0, s[2:3]
	global_store_dwordx4 v[10:11], v[212:215], off
.Lbnd_done:
	s_or_b64 exec, exec, s[4:5]
	v_and_b32_e32 v0, 63, v241
	v_lshrrev_b32_e32 v2, 6, v241
	v_cmp_gt_u32_e32 vcc, 44, v0
	v_cmp_lt_u32_e64 s[2:3], 5, v2
	s_and_b64 vcc, vcc, s[2:3]
	v_subrev_u32_e32 v2, 6, v2
	v_mad_u32_u24 v0, v2, 44, v0
	s_mul_i32 s2, s84, 0x58
	s_add_i32 s2, s2, 0x58000
	v_add_u32_e32 v0, s2, v0
	s_and_saveexec_b64 s[4:5], vcc
	s_cbranch_execz .LBB0_193
	s_load_dwordx4 s[8:11], s[54:55], 0xb8
	s_load_dwordx2 s[2:3], s[54:55], 0x30
	s_lshl_b32 s34, s40, 9
	s_add_u32 s6, s82, 0xd200000
	v_readlane_b32 s14, v253, 41
	s_addc_u32 s7, s83, 0
	s_mul_i32 s13, s14, 0x10800
	s_mul_hi_i32 s12, s14, 0x10800
	s_waitcnt lgkmcnt(0)
	s_add_u32 s8, s8, s13
	s_addc_u32 s9, s9, s12
	s_mul_i32 s13, s14, 0x5800
	s_mul_hi_i32 s12, s14, 0x5800
	s_add_u32 s10, s10, s13
	s_addc_u32 s11, s11, s12
	s_mul_i32 s12, s14, 0x580000
	s_mul_hi_i32 s13, s14, 0x580000
	s_add_u32 s12, s2, s12
	s_addc_u32 s13, s3, s13
	s_add_u32 s14, s10, 0x2c00
	s_addc_u32 s15, s11, 0
	s_add_u32 s16, s8, 0x2c00
	s_addc_u32 s17, s9, 0
	s_add_u32 s18, s8, 0x5800
	s_addc_u32 s19, s9, 0
	s_add_u32 s20, s8, 0x8400
	s_addc_u32 s21, s9, 0
	s_add_u32 s22, s8, 0xb000
	s_addc_u32 s23, s9, 0
	s_add_u32 s24, s8, 0xdc00
	v_mov_b32_e32 v98, 0
	s_addc_u32 s25, s9, 0
	v_lshlrev_b32_e32 v5, 3, v0
	s_lshl_b32 s35, s40, 12
	s_mov_b64 s[26:27], 0
	v_mov_b32_e32 v99, v98
	v_mov_b32_e32 v100, v98
	v_mov_b32_e32 v101, v98
	s_waitcnt vmcnt(0)
	v_mov_b32_e32 v86, v98
	v_mov_b32_e32 v87, v98
	v_mov_b32_e32 v88, v98
	v_mov_b32_e32 v89, v98
	v_mov_b32_e32 v106, v98
	v_mov_b32_e32 v107, v98
	v_mov_b32_e32 v108, v98
	v_mov_b32_e32 v109, v98
	v_mov_b32_e32 v102, v98
	v_mov_b32_e32 v103, v98
	v_mov_b32_e32 v104, v98
	v_mov_b32_e32 v105, v98
	s_branch .LBB0_185
